# attention LDS-store address arithmetic: quarter-rate v_mul_lo_u32 (row*400, row*144) -> full-rate v_mul_u32_u24
# speedup vs baseline: 1.0059x; 1.0054x over previous
.LBB0_938:
	v_mov_b32_e32 v199, v218
	s_lshl_b32 s1, s48, 8
	v_readfirstlane_b32 s0, v199
	s_and_b32 s49, s1, 0x300
	s_ashr_i32 s0, s0, 1
	s_xor_b32 s17, s49, 0x700
	s_and_b32 s57, s0, 0xffffffe0
	s_ashr_i32 s10, s48, 5
	v_and_b32_e32 v20, 31, v199
	s_add_i32 s57, s57, s17
	s_ashr_i32 s11, s10, 31
	v_or_b32_e32 v196, s57, v20
	s_lshl_b64 s[30:31], s[10:11], 11
	v_ashrrev_i32_e32 v197, 31, v196
	v_lshl_add_u64 v[194:195], s[30:31], 0, v[196:197]
	v_mov_b64_e32 v[0:1], s[8:9]
	v_mad_u64_u32 v[0:1], s[0:1], v194, s50, v[0:1]
	s_bfe_u32 s16, s48, 0x30002
	s_lshl_b64 s[18:19], s[10:11], 22
	s_lshl_b64 s[0:1], s[10:11], 18
	s_lshl_b32 s10, s10, 3
	s_mul_i32 s52, s16, 0xc0
	s_or_b32 s10, s10, s16
	v_bfe_u32 v21, v199, 5, 1
	v_mad_i32_i24 v1, v195, s50, v1
	s_lshl_b32 s64, s52, 1
	s_ashr_i32 s11, s10, 31
	v_lshl_add_u64 v[0:1], v[0:1], 0, s[64:65]
	v_lshlrev_b32_e32 v180, 4, v21
	s_lshl_b32 s56, s16, 7
	s_lshl_b64 s[20:21], s[10:11], 19
	s_addk_i32 s17, 0x100
	v_lshl_add_u64 v[0:1], v[0:1], 0, v[180:181]
	s_add_u32 s10, s4, s18
	global_load_dwordx4 v[112:115], v[0:1], off
	global_load_dwordx4 v[116:119], v[0:1], off offset:32
	global_load_dwordx4 v[120:123], v[0:1], off offset:64
	global_load_dwordx4 v[124:127], v[0:1], off offset:96
	global_load_dwordx4 v[128:131], v[0:1], off offset:128
	global_load_dwordx4 v[132:135], v[0:1], off offset:160
	global_load_dwordx4 v[136:139], v[0:1], off offset:192
	global_load_dwordx4 v[140:143], v[0:1], off offset:224
	global_load_dwordx4 v[144:147], v[0:1], off offset:256
	global_load_dwordx4 v[148:151], v[0:1], off offset:288
	global_load_dwordx4 v[152:155], v[0:1], off offset:320
	global_load_dwordx4 v[156:159], v[0:1], off offset:352
	s_addc_u32 s11, s33, s19
	s_lshl_b32 s16, s16, 8
	s_add_u32 s22, s10, s16
	v_mov_b32_e32 v0, v199
	s_addc_u32 s23, s11, 0
	s_add_u32 s24, s46, s20
	v_lshrrev_b32_e32 v1, 3, v0
	v_lshlrev_b32_e32 v0, 4, v0
	s_addc_u32 s25, s47, s21
	v_and_b32_e32 v0, 0x70, v0
	s_add_u32 s26, s44, s0
	v_lshl_or_b32 v4, v1, 11, v0
	v_lshl_or_b32 v8, v1, 7, v0
	s_addc_u32 s27, s45, s1
	v_lshl_or_b32 v16, v1, 12, v0
	global_load_dwordx4 v[0:3], v4, s[22:23]
	s_nop 0
	global_load_dwordx4 v[4:7], v4, s[22:23] offset:128
	s_nop 0
	global_load_dwordx4 v[8:11], v8, s[26:27]
	s_nop 0
	global_load_dwordx4 v[12:15], v16, s[24:25]
	s_lshr_b32 s58, s17, 6
	s_add_u32 s34, s24, 0x40000
	s_addc_u32 s35, s25, 0
	global_load_dwordx4 v[16:19], v16, s[34:35]
	v_mov_b32_e32 v22, v199
	v_mad_u32_u24 v23, v20, s51, 0
	v_lshrrev_b32_e32 v24, 3, v22
	v_lshlrev_b32_e32 v25, 4, v22
	v_lshlrev_b32_e32 v22, 3, v22
	v_mul_u32_u24_e32 v26, s51, v24
	v_mul_u32_u24_e32 v24, s5, v24
	v_and_b32_e32 v27, 0x70, v25
	v_and_b32_e32 v25, 0x60, v25
	v_and_b32_e32 v22, 8, v22
	v_add_u32_e32 v24, 0, v24
	v_add3_u32 v26, 0, v26, v27
	v_add3_u32 v22, v24, v25, v22
	s_or_b32 s59, s57, 31
	v_add_u32_e32 v24, 0x6000, v22
	v_add_u32_e32 v22, 0x8800, v22
	s_add_i32 s61, s58, -1
	s_add_u32 s28, s0, 0x12902000
	v_mov_b32_e32 v48, v181
	v_mov_b32_e32 v49, v181
	v_mov_b32_e32 v62, v181
	v_mov_b32_e32 v63, v181
	v_lshlrev_b32_e32 v198, 3, v21
	v_lshlrev_b32_e32 v197, 2, v21
	s_addc_u32 s29, s1, 0
	s_or_b32 s18, s18, s16
	v_mov_b32_e32 v50, v181
	v_mov_b32_e32 v51, v181
	v_mov_b32_e32 v52, v181
	v_mov_b32_e32 v53, v181
	v_mov_b32_e32 v54, v181
	v_mov_b32_e32 v55, v181
	v_mov_b32_e32 v56, v181
	v_mov_b32_e32 v57, v181
	v_mov_b32_e32 v58, v181
	v_mov_b32_e32 v59, v181
	v_mov_b32_e32 v60, v181
	v_mov_b32_e32 v61, v181
	v_add_u32_e32 v205, v23, v180
	v_mov_b64_e32 v[32:33], v[48:49]
	v_mov_b64_e32 v[78:79], v[62:63]
	s_waitcnt vmcnt(4)
	ds_write_b128 v26, v[0:3]
	s_waitcnt vmcnt(3)
	ds_write_b128 v26, v[4:7] offset:128
	s_waitcnt vmcnt(2)
	ds_write_b128 v26, v[8:11] offset:256
	s_waitcnt vmcnt(1)
	ds_write2_b64 v24, v[12:13], v[14:15] offset0:128 offset1:130
	s_waitcnt vmcnt(0)
	ds_write2_b64 v22, v[16:17], v[18:19] offset1:2
	v_lshlrev_b32_e32 v0, 8, v20
	v_mov_b32_e32 v1, s63
	v_sub_u32_e32 v0, v23, v0
	v_mad_u32_u24 v1, v20, s5, v1
	v_add_u32_e32 v207, v0, v180
	v_add_u32_e32 v208, v1, v180
	v_mov_b64_e32 v[16:17], v[48:49]
	v_mov_b64_e32 v[0:1], v[48:49]
	s_mov_b32 s60, 2
	v_mov_b32_e32 v206, 0
	s_mov_b32 s62, 63
	s_mov_b64 s[0:1], s[18:19]
	s_mov_b64 s[36:37], s[28:29]
	s_mov_b64 s[38:39], s[20:21]
	v_mov_b64_e32 v[34:35], v[50:51]
	v_mov_b64_e32 v[36:37], v[52:53]
	v_mov_b64_e32 v[38:39], v[54:55]
	v_mov_b64_e32 v[40:41], v[56:57]
	v_mov_b64_e32 v[42:43], v[58:59]
	v_mov_b64_e32 v[44:45], v[60:61]
	v_mov_b64_e32 v[46:47], v[62:63]
	v_mov_b64_e32 v[18:19], v[50:51]
	v_mov_b64_e32 v[20:21], v[52:53]
	v_mov_b64_e32 v[22:23], v[54:55]
	v_mov_b64_e32 v[24:25], v[56:57]
	v_mov_b64_e32 v[26:27], v[58:59]
	v_mov_b64_e32 v[28:29], v[60:61]
	v_mov_b64_e32 v[30:31], v[62:63]
	v_mov_b64_e32 v[2:3], v[50:51]
	v_mov_b64_e32 v[4:5], v[52:53]
	v_mov_b64_e32 v[6:7], v[54:55]
	v_mov_b64_e32 v[8:9], v[56:57]
	v_mov_b64_e32 v[10:11], v[58:59]
	v_mov_b64_e32 v[12:13], v[60:61]
	v_mov_b64_e32 v[14:15], v[62:63]
	v_mov_b32_e32 v209, 0
	v_mov_b64_e32 v[76:77], v[60:61]
	v_mov_b64_e32 v[74:75], v[58:59]
	v_mov_b64_e32 v[72:73], v[56:57]
	v_mov_b64_e32 v[70:71], v[54:55]
	v_mov_b64_e32 v[68:69], v[52:53]
	v_mov_b64_e32 v[66:67], v[50:51]
	v_mov_b64_e32 v[64:65], v[48:49]
	v_mov_b32_e32 v80, v199
	s_add_u32 s98, s6, s0
	v_lshrrev_b32_e32 v81, 3, v80
	v_lshlrev_b32_e32 v80, 4, v80
	v_and_b32_e32 v80, 0x70, v80
	v_lshl_or_b32 v180, v81, 11, v80
	s_addc_u32 s99, s7, s1
	v_lshl_add_u64 v[82:83], s[98:99], 0, v[180:181]
	v_add_co_u32_e32 v82, vcc, s53, v82
	s_add_u32 s98, s6, s36
	s_nop 0
	v_addc_co_u32_e32 v83, vcc, 0, v83, vcc
	s_addc_u32 s99, s7, s37
	v_lshl_or_b32 v84, v81, 7, v80
	global_load_dwordx4 v[160:163], v[82:83], off
	global_load_dwordx4 v[164:167], v84, s[98:99]
	s_add_u32 s98, s6, s38
	v_lshl_or_b32 v80, v81, 12, v80
	v_mov_b32_e32 v81, v181
	s_addc_u32 s99, s7, s39
	v_lshl_add_u64 v[80:81], s[98:99], 0, v[80:81]
	v_add_co_u32_e32 v84, vcc, 0xe900000, v80
	s_nop 0
	v_addc_co_u32_e32 v85, vcc, 0, v81, vcc
	v_add_co_u32_e32 v80, vcc, 0xe940000, v80
	global_load_dwordx4 v[176:179], v[82:83], off offset:128
	global_load_dwordx4 v[168:171], v[84:85], off offset:128
	v_addc_co_u32_e32 v81, vcc, 0, v81, vcc
	global_load_dwordx4 v[172:175], v[80:81], off offset:128
	s_waitcnt lgkmcnt(0)
	s_barrier
	s_branch .LBB0_940

.LBB0_951:
	v_mov_b32_e32 v80, v199
	s_min_u32 s64, s60, s61
	v_lshrrev_b32_e32 v81, 3, v80
	v_lshlrev_b32_e32 v83, 4, v80
	v_mul_u32_u24_e32 v82, s51, v81
	v_and_b32_e32 v84, 0x70, v83
	v_mul_u32_u24_e32 v81, s5, v81
	v_and_b32_e32 v83, 0x60, v83
	v_lshlrev_b32_e32 v80, 3, v80
	v_and_b32_e32 v80, 8, v80
	v_add3_u32 v81, 0, v81, v83
	v_add3_u32 v80, v81, v80, s55
	s_lshl_b64 s[10:11], s[64:65], 17
	v_add3_u32 v82, 0, v82, v84
	v_add_u32_e32 v81, 0x6000, v80
	v_add_u32_e32 v80, 0x8800, v80
	s_add_u32 s10, s22, s10
	s_waitcnt vmcnt(4)
	ds_write_b128 v82, v[160:163] offset:44032
	s_waitcnt vmcnt(2)
	ds_write_b128 v82, v[176:179] offset:44160
	ds_write_b128 v82, v[164:167] offset:44288
	s_waitcnt vmcnt(0)
	ds_write2_b64 v80, v[172:173], v[174:175] offset1:2
	v_mov_b32_e32 v80, v199
	s_addc_u32 s11, s23, s11
	s_lshl_b64 s[16:17], s[64:65], 13
	ds_write2_b64 v81, v[168:169], v[170:171] offset0:128 offset1:130
	s_add_u32 s16, s26, s16
	v_lshrrev_b32_e32 v81, 3, v80
	v_lshlrev_b32_e32 v80, 4, v80
	s_addc_u32 s17, s27, s17
	s_lshl_b64 s[40:41], s[64:65], 7
	v_and_b32_e32 v80, 0x70, v80
	s_add_u32 s40, s24, s40
	v_lshl_or_b32 v180, v81, 12, v80
	s_addc_u32 s41, s25, s41
	v_lshl_or_b32 v82, v81, 11, v80
	v_lshl_or_b32 v83, v81, 7, v80
	v_lshl_add_u64 v[80:81], s[40:41], 0, v[180:181]
	v_add_co_u32_e32 v80, vcc, 0x40000, v80
	global_load_dwordx4 v[168:171], v82, s[10:11]
	global_load_dwordx4 v[172:175], v82, s[10:11] offset:128
	global_load_dwordx4 v[160:163], v180, s[40:41]
	v_addc_co_u32_e32 v81, vcc, 0, v81, vcc
	global_load_dwordx4 v[176:179], v83, s[16:17]
	global_load_dwordx4 v[164:167], v[80:81], off
	s_waitcnt lgkmcnt(0)
	s_barrier
	s_add_i32 s10, s62, 1
	s_cmp_gt_i32 s10, s59
	s_cbranch_scc1 .LBB0_957
	ds_read_b128 v[80:83], v205 offset:44032
	ds_read_b128 v[210:213], v205 offset:44064
	ds_read_b128 v[214:217], v205 offset:56832
	ds_read_b128 v[220:223], v205 offset:56864
	s_waitcnt lgkmcnt(3)
	v_mfma_f32_32x32x16_bf16 v[96:111], v[80:83], v[112:115], v[64:79]
	s_waitcnt lgkmcnt(1)
	v_mfma_f32_32x32x16_bf16 v[80:95], v[214:217], v[112:115], v[64:79]
	ds_read_b128 v[214:217], v205 offset:44096
	ds_read_b128 v[224:227], v205 offset:56896
	v_mfma_f32_32x32x16_bf16 v[96:111], v[210:213], v[116:119], v[96:111]
	s_waitcnt lgkmcnt(2)
	v_mfma_f32_32x32x16_bf16 v[80:95], v[220:223], v[116:119], v[80:95]
	ds_read_b128 v[210:213], v205 offset:44128
	ds_read_b128 v[220:223], v205 offset:56928
	s_waitcnt lgkmcnt(3)
	v_mfma_f32_32x32x16_bf16 v[96:111], v[214:217], v[120:123], v[96:111]
	s_waitcnt lgkmcnt(2)
	v_mfma_f32_32x32x16_bf16 v[80:95], v[224:227], v[120:123], v[80:95]
	ds_read_b128 v[214:217], v205 offset:44160
	ds_read_b128 v[224:227], v205 offset:56960
	s_waitcnt lgkmcnt(3)
	v_mfma_f32_32x32x16_bf16 v[96:111], v[210:213], v[124:127], v[96:111]
	s_waitcnt lgkmcnt(2)
	v_mfma_f32_32x32x16_bf16 v[80:95], v[220:223], v[124:127], v[80:95]
	ds_read_b128 v[210:213], v205 offset:44192
	ds_read_b128 v[220:223], v205 offset:56992
	s_waitcnt lgkmcnt(3)
	v_mfma_f32_32x32x16_bf16 v[96:111], v[214:217], v[128:131], v[96:111]
	s_waitcnt lgkmcnt(2)
	v_mfma_f32_32x32x16_bf16 v[80:95], v[224:227], v[128:131], v[80:95]
	ds_read_b128 v[214:217], v205 offset:44224
	ds_read_b128 v[224:227], v205 offset:57024
	s_waitcnt lgkmcnt(3)
	v_mfma_f32_32x32x16_bf16 v[96:111], v[210:213], v[132:135], v[96:111]
	s_waitcnt lgkmcnt(2)
	v_mfma_f32_32x32x16_bf16 v[80:95], v[220:223], v[132:135], v[80:95]
	ds_read_b128 v[210:213], v205 offset:44256
	ds_read_b128 v[220:223], v205 offset:57056
	s_waitcnt lgkmcnt(3)
	v_mfma_f32_32x32x16_bf16 v[96:111], v[214:217], v[136:139], v[96:111]
	s_waitcnt lgkmcnt(2)
	v_mfma_f32_32x32x16_bf16 v[80:95], v[224:227], v[136:139], v[80:95]
	ds_read_b128 v[214:217], v205 offset:44288
	ds_read_b128 v[224:227], v205 offset:57088
	s_waitcnt lgkmcnt(3)
	v_mfma_f32_32x32x16_bf16 v[96:111], v[210:213], v[140:143], v[96:111]
	s_waitcnt lgkmcnt(2)
	v_mfma_f32_32x32x16_bf16 v[80:95], v[220:223], v[140:143], v[80:95]
	ds_read_b128 v[210:213], v205 offset:44320
	ds_read_b128 v[220:223], v205 offset:57120
	s_waitcnt lgkmcnt(3)
	v_mfma_f32_32x32x16_bf16 v[96:111], v[214:217], v[144:147], v[96:111]
	s_waitcnt lgkmcnt(2)
	v_mfma_f32_32x32x16_bf16 v[80:95], v[224:227], v[144:147], v[80:95]
	ds_read_b128 v[214:217], v205 offset:44352
	ds_read_b128 v[224:227], v205 offset:57152
	s_waitcnt lgkmcnt(3)
	v_mfma_f32_32x32x16_bf16 v[96:111], v[210:213], v[148:151], v[96:111]
	s_waitcnt lgkmcnt(2)
	v_mfma_f32_32x32x16_bf16 v[80:95], v[220:223], v[148:151], v[80:95]
	ds_read_b128 v[210:213], v205 offset:44384
	ds_read_b128 v[220:223], v205 offset:57184
	s_waitcnt lgkmcnt(3)
	v_mfma_f32_32x32x16_bf16 v[96:111], v[214:217], v[152:155], v[96:111]
	s_waitcnt lgkmcnt(2)
	v_mfma_f32_32x32x16_bf16 v[80:95], v[224:227], v[152:155], v[80:95]
	s_waitcnt lgkmcnt(1)
	v_mfma_f32_32x32x16_bf16 v[96:111], v[210:213], v[156:159], v[96:111]
	s_waitcnt lgkmcnt(0)
	v_mfma_f32_32x32x16_bf16 v[80:95], v[220:223], v[156:159], v[80:95]
	s_add_i32 s10, s62, 64
	s_cmp_le_i32 s10, s57
	s_nop 15
	s_nop 7
	s_cbranch_scc1 .LBB0_954
	v_add_u32_e32 v180, s62, v197
	v_add_u32_e32 v203, 33, v180
	v_add_u32_e32 v202, 1, v180
	v_cmp_le_i32_e32 vcc, v203, v196
	s_nop 4
	v_cndmask_b32_e32 v80, v204, v80, vcc
	v_cmp_lt_i32_e32 vcc, v202, v196
	s_nop 1
	v_cndmask_b32_e32 v97, v204, v97, vcc
	v_cmp_le_i32_e32 vcc, v202, v196
	v_add_u32_e32 v202, 34, v180
	s_nop 0
	v_cndmask_b32_e32 v96, v204, v96, vcc
	v_cmp_le_i32_e32 vcc, v202, v196
	v_add_u32_e32 v202, 3, v180
	s_nop 0
	v_cndmask_b32_e32 v81, v204, v81, vcc
	v_cmp_le_i32_e32 vcc, v202, v196
	v_add_u32_e32 v202, 35, v180
	s_nop 0
	v_cndmask_b32_e32 v98, v204, v98, vcc
	v_cmp_le_i32_e32 vcc, v202, v196
	v_add_u32_e32 v202, 4, v180
	s_nop 0
	v_cndmask_b32_e32 v82, v204, v82, vcc
	v_cmp_le_i32_e32 vcc, v202, v196
	v_add_u32_e32 v202, 36, v180
	s_nop 0
	v_cndmask_b32_e32 v99, v204, v99, vcc
	v_cmp_le_i32_e32 vcc, v202, v196
	v_add_u32_e32 v202, 9, v180
	s_nop 0
	v_cndmask_b32_e32 v83, v204, v83, vcc
	v_cmp_le_i32_e32 vcc, v202, v196
	v_add_u32_e32 v202, 41, v180
	s_nop 0
	v_cndmask_b32_e32 v100, v204, v100, vcc
	v_cmp_le_i32_e32 vcc, v202, v196
	v_add_u32_e32 v202, 10, v180
	s_nop 0
	v_cndmask_b32_e32 v84, v204, v84, vcc
	v_cmp_le_i32_e32 vcc, v202, v196
	v_add_u32_e32 v202, 42, v180
	s_nop 0
	v_cndmask_b32_e32 v101, v204, v101, vcc
	v_cmp_le_i32_e32 vcc, v202, v196
	v_add_u32_e32 v202, 11, v180
	s_nop 0
	v_cndmask_b32_e32 v85, v204, v85, vcc
	v_cmp_le_i32_e32 vcc, v202, v196
	v_add_u32_e32 v202, 43, v180
	s_nop 0
	v_cndmask_b32_e32 v102, v204, v102, vcc
	v_cmp_le_i32_e32 vcc, v202, v196
	v_add_u32_e32 v202, 12, v180
	s_nop 0
	v_cndmask_b32_e32 v86, v204, v86, vcc
	v_cmp_le_i32_e32 vcc, v202, v196
	v_add_u32_e32 v202, 44, v180
	s_nop 0
	v_cndmask_b32_e32 v103, v204, v103, vcc
	v_cmp_le_i32_e32 vcc, v202, v196
	v_add_u32_e32 v202, 17, v180
	s_nop 0
	v_cndmask_b32_e32 v87, v204, v87, vcc
	v_cmp_le_i32_e32 vcc, v202, v196
	v_add_u32_e32 v202, 49, v180
	s_nop 0
	v_cndmask_b32_e32 v104, v204, v104, vcc
	v_cmp_le_i32_e32 vcc, v202, v196
	v_add_u32_e32 v202, 18, v180
	s_nop 0
	v_cndmask_b32_e32 v88, v204, v88, vcc
	v_cmp_le_i32_e32 vcc, v202, v196
	v_add_u32_e32 v202, 50, v180
	s_nop 0
	v_cndmask_b32_e32 v105, v204, v105, vcc
	v_cmp_le_i32_e32 vcc, v202, v196
	v_add_u32_e32 v202, 19, v180
	s_nop 0
	v_cndmask_b32_e32 v89, v204, v89, vcc
	v_cmp_le_i32_e32 vcc, v202, v196
	v_add_u32_e32 v202, 51, v180
	s_nop 0
	v_cndmask_b32_e32 v106, v204, v106, vcc
	v_cmp_le_i32_e32 vcc, v202, v196
	v_add_u32_e32 v202, 20, v180
	s_nop 0
	v_cndmask_b32_e32 v90, v204, v90, vcc
	v_cmp_le_i32_e32 vcc, v202, v196
	v_add_u32_e32 v202, 52, v180
	s_nop 0
	v_cndmask_b32_e32 v107, v204, v107, vcc
	v_cmp_le_i32_e32 vcc, v202, v196
	v_add_u32_e32 v202, 25, v180
	s_nop 0
	v_cndmask_b32_e32 v91, v204, v91, vcc
	v_cmp_le_i32_e32 vcc, v202, v196
	v_add_u32_e32 v202, 57, v180
	s_nop 0
	v_cndmask_b32_e32 v108, v204, v108, vcc
	v_cmp_le_i32_e32 vcc, v202, v196
	v_add_u32_e32 v202, 26, v180
	s_nop 0
	v_cndmask_b32_e32 v92, v204, v92, vcc
	v_cmp_le_i32_e32 vcc, v202, v196
	v_add_u32_e32 v202, 58, v180
	s_nop 0
	v_cndmask_b32_e32 v109, v204, v109, vcc
	v_cmp_le_i32_e32 vcc, v202, v196
	v_add_u32_e32 v202, 27, v180
	s_nop 0
	v_cndmask_b32_e32 v93, v204, v93, vcc
	v_cmp_le_i32_e32 vcc, v202, v196
	v_add_u32_e32 v202, 59, v180
	s_nop 0
	v_cndmask_b32_e32 v110, v204, v110, vcc
	v_cmp_le_i32_e32 vcc, v202, v196
	v_add_u32_e32 v202, 28, v180
	v_add_u32_e32 v180, 60, v180
	v_cndmask_b32_e32 v94, v204, v94, vcc
	v_cmp_le_i32_e32 vcc, v202, v196
	s_nop 1
	v_cndmask_b32_e32 v111, v204, v111, vcc
	v_cmp_le_i32_e32 vcc, v180, v196
	s_nop 1
	v_cndmask_b32_e32 v95, v204, v95, vcc

.LBB0_957:
	s_cmp_ge_u32 s60, s58
	s_cselect_b64 s[10:11], -1, 0
	s_and_b64 vcc, exec, s[10:11]
	s_cbranch_vccnz .LBB0_939
	v_mov_b32_e32 v80, v199
	s_nop 0
	v_lshrrev_b32_e32 v81, 3, v80
	v_mul_u32_u24_e32 v82, s51, v81
	v_lshlrev_b32_e32 v83, 4, v80
	v_mul_u32_u24_e32 v81, s5, v81
	v_lshlrev_b32_e32 v80, 3, v80
	v_and_b32_e32 v84, 0x70, v83
	v_and_b32_e32 v83, 0x60, v83
	v_and_b32_e32 v80, 8, v80
	v_add_u32_e32 v81, 0, v81
	v_add3_u32 v80, v81, v83, v80
	v_add3_u32 v82, 0, v82, v84
	v_add_u32_e32 v81, 0x6000, v80
	v_add_u32_e32 v80, 0x8800, v80
	s_waitcnt vmcnt(4)
	ds_write_b128 v82, v[168:171]
	s_waitcnt vmcnt(3)
	ds_write_b128 v82, v[172:175] offset:128
	s_waitcnt vmcnt(1)
	ds_write_b128 v82, v[176:179] offset:256
	ds_write2_b64 v81, v[160:161], v[162:163] offset0:128 offset1:130
	s_waitcnt vmcnt(0)
	ds_write2_b64 v80, v[164:165], v[166:167] offset1:2
	s_branch .LBB0_939

.LBB0_960:
	v_and_b32_e32 v65, 64, v219
	v_xor_b32_e32 v64, 32, v219
	v_add_u32_e32 v65, 64, v65
	v_cmp_lt_i32_e32 vcc, v64, v65
	v_lshlrev_b32_e32 v180, 1, v198
	s_lshl_b32 s64, s52, 1
	v_cndmask_b32_e32 v64, v219, v64, vcc
	v_lshlrev_b32_e32 v205, 2, v64
	v_mov_b32_e32 v64, v206
	v_mov_b32_e32 v251, v206
	s_nop 1
	v_permlane32_swap_b32_e32 v64, v251
	v_readlane_b32 s58, v255, 3
	v_readlane_b32 s60, v253, 16
	s_mov_b32 s36, 2
	s_mov_b32 s40, 63
	s_waitcnt lgkmcnt(0)
	v_add_f32_e32 v66, v64, v251
	v_div_scale_f32 v67, s[0:1], v66, v66, 1.0
	v_rcp_f32_e32 v68, v67
	v_div_scale_f32 v69, vcc, 1.0, v66, 1.0
	v_lshlrev_b64 v[64:65], 11, v[194:195]
	v_fma_f32 v70, -v67, v68, 1.0
	v_fmac_f32_e32 v68, v70, v68
	v_mul_f32_e32 v70, v69, v68
	v_fma_f32 v71, -v67, v70, v69
	v_fmac_f32_e32 v70, v71, v68
	v_fma_f32 v67, -v67, v70, v69
	v_div_fmas_f32 v67, v67, v68, v70
	v_div_fixup_f32 v66, v67, v66, 1.0
	v_pk_mul_f32 v[48:49], v[48:49], v[66:67] op_sel_hi:[1,0]
	v_pk_mul_f32 v[50:51], v[50:51], v[66:67] op_sel_hi:[1,0]
	v_pk_mul_f32 v[32:33], v[32:33], v[66:67] op_sel_hi:[1,0]
	v_pk_mul_f32 v[34:35], v[34:35], v[66:67] op_sel_hi:[1,0]
	v_pk_mul_f32 v[16:17], v[16:17], v[66:67] op_sel_hi:[1,0]
	v_pk_mul_f32 v[18:19], v[18:19], v[66:67] op_sel_hi:[1,0]
	v_pk_mul_f32 v[0:1], v[0:1], v[66:67] op_sel_hi:[1,0]
	v_pk_mul_f32 v[2:3], v[2:3], v[66:67] op_sel_hi:[1,0]
	v_lshl_add_u64 v[64:65], s[14:15], 0, v[64:65]
	s_lshl_b32 s0, s56, 1
	s_mov_b32 s1, s65
	v_cvt_pk_bf16_f32 v48, v48, v49
	v_cvt_pk_bf16_f32 v49, v50, v51
	v_pk_mul_f32 v[50:51], v[52:53], v[66:67] op_sel_hi:[1,0]
	v_pk_mul_f32 v[52:53], v[54:55], v[66:67] op_sel_hi:[1,0]
	v_cvt_pk_bf16_f32 v32, v32, v33
	v_cvt_pk_bf16_f32 v33, v34, v35
	v_pk_mul_f32 v[34:35], v[36:37], v[66:67] op_sel_hi:[1,0]
	v_pk_mul_f32 v[36:37], v[38:39], v[66:67] op_sel_hi:[1,0]
	v_cvt_pk_bf16_f32 v16, v16, v17
	v_cvt_pk_bf16_f32 v17, v18, v19
	v_pk_mul_f32 v[18:19], v[20:21], v[66:67] op_sel_hi:[1,0]
	v_pk_mul_f32 v[20:21], v[22:23], v[66:67] op_sel_hi:[1,0]
	v_cvt_pk_bf16_f32 v0, v0, v1
	v_cvt_pk_bf16_f32 v1, v2, v3
	v_pk_mul_f32 v[2:3], v[4:5], v[66:67] op_sel_hi:[1,0]
	v_pk_mul_f32 v[4:5], v[6:7], v[66:67] op_sel_hi:[1,0]
	v_lshl_add_u64 v[64:65], v[64:65], 0, s[0:1]
	v_cvt_pk_bf16_f32 v50, v50, v51
	v_cvt_pk_bf16_f32 v51, v52, v53
	v_cvt_pk_bf16_f32 v34, v34, v35
	v_cvt_pk_bf16_f32 v35, v36, v37
	v_cvt_pk_bf16_f32 v18, v18, v19
	v_cvt_pk_bf16_f32 v19, v20, v21
	v_cvt_pk_bf16_f32 v2, v2, v3
	v_cvt_pk_bf16_f32 v3, v4, v5
	v_lshl_add_u64 v[64:65], v[64:65], 0, v[180:181]
	v_permlane32_swap_b32_e32 v48, v50
	v_permlane32_swap_b32_e32 v49, v51
	v_permlane32_swap_b32_e32 v32, v34
	v_permlane32_swap_b32_e32 v33, v35
	v_permlane32_swap_b32_e32 v16, v18
	v_permlane32_swap_b32_e32 v17, v19
	v_permlane32_swap_b32_e32 v0, v2
	v_permlane32_swap_b32_e32 v1, v3
	global_store_dwordx4 v[64:65], v[48:51], off
	global_store_dwordx4 v[64:65], v[32:35], off offset:64
	global_store_dwordx4 v[64:65], v[16:19], off offset:128
	v_pk_mul_f32 v[48:49], v[56:57], v[66:67] op_sel_hi:[1,0]
	v_pk_mul_f32 v[50:51], v[58:59], v[66:67] op_sel_hi:[1,0]
	v_pk_mul_f32 v[32:33], v[40:41], v[66:67] op_sel_hi:[1,0]
	v_pk_mul_f32 v[34:35], v[42:43], v[66:67] op_sel_hi:[1,0]
	v_pk_mul_f32 v[16:17], v[24:25], v[66:67] op_sel_hi:[1,0]
	v_pk_mul_f32 v[18:19], v[26:27], v[66:67] op_sel_hi:[1,0]
	global_store_dwordx4 v[64:65], v[0:3], off offset:192
	v_cvt_pk_bf16_f32 v48, v48, v49
	v_cvt_pk_bf16_f32 v49, v50, v51
	v_pk_mul_f32 v[0:1], v[8:9], v[66:67] op_sel_hi:[1,0]
	v_pk_mul_f32 v[2:3], v[10:11], v[66:67] op_sel_hi:[1,0]
	v_pk_mul_f32 v[50:51], v[60:61], v[66:67] op_sel_hi:[1,0]
	v_pk_mul_f32 v[52:53], v[62:63], v[66:67] op_sel_hi:[1,0]
	v_cvt_pk_bf16_f32 v32, v32, v33
	v_cvt_pk_bf16_f32 v33, v34, v35
	v_pk_mul_f32 v[34:35], v[44:45], v[66:67] op_sel_hi:[1,0]
	v_pk_mul_f32 v[36:37], v[46:47], v[66:67] op_sel_hi:[1,0]
	v_cvt_pk_bf16_f32 v16, v16, v17
	v_cvt_pk_bf16_f32 v17, v18, v19
	v_pk_mul_f32 v[18:19], v[28:29], v[66:67] op_sel_hi:[1,0]
	v_pk_mul_f32 v[20:21], v[30:31], v[66:67] op_sel_hi:[1,0]
	v_cvt_pk_bf16_f32 v0, v0, v1
	v_cvt_pk_bf16_f32 v1, v2, v3
	v_pk_mul_f32 v[2:3], v[12:13], v[66:67] op_sel_hi:[1,0]
	v_pk_mul_f32 v[4:5], v[14:15], v[66:67] op_sel_hi:[1,0]
	v_cvt_pk_bf16_f32 v50, v50, v51
	v_cvt_pk_bf16_f32 v51, v52, v53
	v_cvt_pk_bf16_f32 v34, v34, v35
	v_cvt_pk_bf16_f32 v35, v36, v37
	v_cvt_pk_bf16_f32 v18, v18, v19
	v_cvt_pk_bf16_f32 v19, v20, v21
	v_cvt_pk_bf16_f32 v2, v2, v3
	v_cvt_pk_bf16_f32 v3, v4, v5
	v_permlane32_swap_b32_e32 v48, v50
	v_permlane32_swap_b32_e32 v49, v51
	v_permlane32_swap_b32_e32 v32, v34
	v_permlane32_swap_b32_e32 v33, v35
	v_permlane32_swap_b32_e32 v16, v18
	v_permlane32_swap_b32_e32 v17, v19
	v_permlane32_swap_b32_e32 v0, v2
	v_permlane32_swap_b32_e32 v1, v3
	v_mov_b32_e32 v195, v218
	global_store_dwordx4 v[64:65], v[48:51], off offset:32
	global_store_dwordx4 v[64:65], v[32:35], off offset:96
	global_store_dwordx4 v[64:65], v[16:19], off offset:160
	global_store_dwordx4 v[64:65], v[0:3], off offset:224
	v_mov_b32_e32 v48, v181
	v_readfirstlane_b32 s1, v195
	s_ashr_i32 s1, s1, 1
	s_andn2_b32 s1, s1, 31
	v_and_b32_e32 v20, 31, v195
	s_add_i32 s1, s1, s49
	v_or_b32_e32 v198, s1, v20
	v_ashrrev_i32_e32 v199, 31, v198
	v_lshl_add_u64 v[196:197], s[30:31], 0, v[198:199]
	v_mov_b64_e32 v[0:1], s[8:9]
	v_mad_u64_u32 v[0:1], s[10:11], v196, s50, v[0:1]
	v_bfe_u32 v21, v195, 5, 1
	v_mad_i32_i24 v1, v197, s50, v1
	v_lshl_add_u64 v[0:1], v[0:1], 0, s[64:65]
	v_lshlrev_b32_e32 v180, 4, v21
	v_lshl_add_u64 v[0:1], v[0:1], 0, v[180:181]
	global_load_dwordx4 v[112:115], v[0:1], off
	global_load_dwordx4 v[116:119], v[0:1], off offset:32
	global_load_dwordx4 v[120:123], v[0:1], off offset:64
	global_load_dwordx4 v[124:127], v[0:1], off offset:96
	global_load_dwordx4 v[128:131], v[0:1], off offset:128
	global_load_dwordx4 v[132:135], v[0:1], off offset:160
	global_load_dwordx4 v[136:139], v[0:1], off offset:192
	global_load_dwordx4 v[140:143], v[0:1], off offset:224
	global_load_dwordx4 v[144:147], v[0:1], off offset:256
	global_load_dwordx4 v[148:151], v[0:1], off offset:288
	global_load_dwordx4 v[152:155], v[0:1], off offset:320
	global_load_dwordx4 v[156:159], v[0:1], off offset:352
	v_mov_b32_e32 v0, v195
	v_mov_b32_e32 v22, v195
	v_lshrrev_b32_e32 v12, 3, v0
	v_lshlrev_b32_e32 v0, 4, v0
	v_and_b32_e32 v13, 0x70, v0
	v_lshl_or_b32 v4, v12, 11, v13
	v_lshl_or_b32 v8, v12, 7, v13
	global_load_dwordx4 v[0:3], v4, s[22:23]
	s_nop 0
	global_load_dwordx4 v[4:7], v4, s[22:23] offset:128
	s_nop 0
	global_load_dwordx4 v[8:11], v8, s[26:27]
	v_lshl_or_b32 v16, v12, 12, v13
	global_load_dwordx4 v[12:15], v16, s[24:25]
	s_nop 0
	global_load_dwordx4 v[16:19], v16, s[34:35]
	s_addk_i32 s49, 0x100
	v_lshrrev_b32_e32 v23, 3, v22
	v_lshlrev_b32_e32 v25, 4, v22
	v_mul_u32_u24_e32 v24, s51, v23
	v_and_b32_e32 v26, 0x70, v25
	v_mul_u32_u24_e32 v23, s5, v23
	v_lshlrev_b32_e32 v22, 3, v22
	v_add3_u32 v24, 0, v24, v26
	v_and_b32_e32 v25, 0x60, v25
	v_and_b32_e32 v22, 8, v22
	s_waitcnt vmcnt(4)
	ds_write_b128 v24, v[0:3]
	s_waitcnt vmcnt(3)
	ds_write_b128 v24, v[4:7] offset:128
	s_waitcnt vmcnt(2)
	ds_write_b128 v24, v[8:11] offset:256
	v_add_u32_e32 v0, 0, v23
	v_add3_u32 v0, v0, v25, v22
	v_add_u32_e32 v1, 0x6000, v0
	v_add_u32_e32 v0, 0x8800, v0
	s_waitcnt vmcnt(1)
	ds_write2_b64 v1, v[12:13], v[14:15] offset0:128 offset1:130
	s_waitcnt vmcnt(0)
	ds_write2_b64 v0, v[16:17], v[18:19] offset1:2
	v_mad_u32_u24 v0, v20, s51, 0
	v_lshlrev_b32_e32 v1, 8, v20
	v_mov_b32_e32 v2, s63
	v_sub_u32_e32 v1, v0, v1
	v_mad_u32_u24 v2, v20, s5, v2
	v_mov_b32_e32 v49, v181
	v_mov_b32_e32 v62, v181
	v_mov_b32_e32 v63, v181
	v_lshlrev_b32_e32 v194, 3, v21
	s_lshr_b32 s37, s49, 6
	v_lshlrev_b32_e32 v199, 2, v21
	v_mov_b32_e32 v50, v181
	v_mov_b32_e32 v51, v181
	v_mov_b32_e32 v52, v181
	v_mov_b32_e32 v53, v181
	v_mov_b32_e32 v54, v181
	v_mov_b32_e32 v55, v181
	v_mov_b32_e32 v56, v181
	v_mov_b32_e32 v57, v181
	v_mov_b32_e32 v58, v181
	v_mov_b32_e32 v59, v181
	v_mov_b32_e32 v60, v181
	v_mov_b32_e32 v61, v181
	v_add_u32_e32 v207, v0, v180
	v_add_u32_e32 v208, v1, v180
	v_add_u32_e32 v209, v2, v180
	v_mov_b64_e32 v[32:33], v[48:49]
	v_mov_b64_e32 v[16:17], v[48:49]
	v_mov_b64_e32 v[0:1], v[48:49]
	v_mov_b64_e32 v[78:79], v[62:63]
	v_readlane_b32 s56, v255, 1
	s_or_b32 s38, s1, 31
	s_add_i32 s39, s37, -1
	v_mov_b32_e32 v206, 0
	v_mov_b64_e32 v[34:35], v[50:51]
	v_mov_b64_e32 v[36:37], v[52:53]
	v_mov_b64_e32 v[38:39], v[54:55]
	v_mov_b64_e32 v[40:41], v[56:57]
	v_mov_b64_e32 v[42:43], v[58:59]
	v_mov_b64_e32 v[44:45], v[60:61]
	v_mov_b64_e32 v[46:47], v[62:63]
	v_mov_b64_e32 v[18:19], v[50:51]
	v_mov_b64_e32 v[20:21], v[52:53]
	v_mov_b64_e32 v[22:23], v[54:55]
	v_mov_b64_e32 v[24:25], v[56:57]
	v_mov_b64_e32 v[26:27], v[58:59]
	v_mov_b64_e32 v[28:29], v[60:61]
	v_mov_b64_e32 v[30:31], v[62:63]
	v_mov_b64_e32 v[2:3], v[50:51]
	v_mov_b64_e32 v[4:5], v[52:53]
	v_mov_b64_e32 v[6:7], v[54:55]
	v_mov_b64_e32 v[8:9], v[56:57]
	v_mov_b64_e32 v[10:11], v[58:59]
	v_mov_b64_e32 v[12:13], v[60:61]
	v_mov_b64_e32 v[14:15], v[62:63]
	v_mov_b32_e32 v210, 0
	v_mov_b64_e32 v[76:77], v[60:61]
	v_mov_b64_e32 v[74:75], v[58:59]
	v_mov_b64_e32 v[72:73], v[56:57]
	v_mov_b64_e32 v[70:71], v[54:55]
	v_mov_b64_e32 v[68:69], v[52:53]
	v_mov_b64_e32 v[66:67], v[50:51]
	v_mov_b64_e32 v[64:65], v[48:49]
	v_readlane_b32 s57, v255, 2
	v_readlane_b32 s59, v255, 4
	v_readlane_b32 s61, v253, 17
	v_mov_b32_e32 v80, v195
	s_add_u32 s98, s6, s18
	v_lshrrev_b32_e32 v81, 3, v80
	v_lshlrev_b32_e32 v80, 4, v80
	v_and_b32_e32 v80, 0x70, v80
	v_lshl_or_b32 v180, v81, 11, v80
	s_addc_u32 s99, s7, s19
	v_lshl_add_u64 v[82:83], s[98:99], 0, v[180:181]
	v_add_co_u32_e32 v82, vcc, s53, v82
	s_add_u32 s98, s6, s28
	s_nop 0
	v_addc_co_u32_e32 v83, vcc, 0, v83, vcc
	s_addc_u32 s99, s7, s29
	v_lshl_or_b32 v84, v81, 7, v80
	global_load_dwordx4 v[160:163], v[82:83], off
	global_load_dwordx4 v[164:167], v84, s[98:99]
	s_add_u32 s98, s6, s20
	v_lshl_or_b32 v80, v81, 12, v80
	v_mov_b32_e32 v81, v181
	s_addc_u32 s99, s7, s21
	v_lshl_add_u64 v[80:81], s[98:99], 0, v[80:81]
	v_add_co_u32_e32 v84, vcc, 0xe900000, v80
	s_nop 0
	v_addc_co_u32_e32 v85, vcc, 0, v81, vcc
	v_add_co_u32_e32 v80, vcc, 0xe940000, v80
	global_load_dwordx4 v[176:179], v[82:83], off offset:128
	global_load_dwordx4 v[168:171], v[84:85], off offset:128
	v_addc_co_u32_e32 v81, vcc, 0, v81, vcc
	global_load_dwordx4 v[172:175], v[80:81], off offset:128
	s_waitcnt lgkmcnt(0)
	s_barrier
	s_branch .LBB0_962

.LBB0_973:
	v_mov_b32_e32 v80, v195
	s_min_u32 s64, s36, s39
	v_lshrrev_b32_e32 v81, 3, v80
	v_lshlrev_b32_e32 v83, 4, v80
	v_mul_u32_u24_e32 v82, s51, v81
	v_and_b32_e32 v84, 0x70, v83
	v_mul_u32_u24_e32 v81, s5, v81
	v_and_b32_e32 v83, 0x60, v83
	v_lshlrev_b32_e32 v80, 3, v80
	v_and_b32_e32 v80, 8, v80
	v_add3_u32 v81, 0, v81, v83
	v_add3_u32 v80, v81, v80, s55
	s_lshl_b64 s[10:11], s[64:65], 17
	v_add3_u32 v82, 0, v82, v84
	v_add_u32_e32 v81, 0x6000, v80
	v_add_u32_e32 v80, 0x8800, v80
	s_add_u32 s10, s22, s10
	s_waitcnt vmcnt(4)
	ds_write_b128 v82, v[160:163] offset:44032
	s_waitcnt vmcnt(2)
	ds_write_b128 v82, v[176:179] offset:44160
	ds_write_b128 v82, v[164:167] offset:44288
	s_waitcnt vmcnt(0)
	ds_write2_b64 v80, v[172:173], v[174:175] offset1:2
	v_mov_b32_e32 v80, v195
	s_addc_u32 s11, s23, s11
	s_lshl_b64 s[16:17], s[64:65], 13
	ds_write2_b64 v81, v[168:169], v[170:171] offset0:128 offset1:130
	s_add_u32 s16, s26, s16
	v_lshrrev_b32_e32 v81, 3, v80
	v_lshlrev_b32_e32 v80, 4, v80
	s_addc_u32 s17, s27, s17
	s_lshl_b64 s[30:31], s[64:65], 7
	v_and_b32_e32 v80, 0x70, v80
	s_add_u32 s30, s24, s30
	v_lshl_or_b32 v180, v81, 12, v80
	s_addc_u32 s31, s25, s31
	v_lshl_or_b32 v82, v81, 11, v80
	v_lshl_or_b32 v83, v81, 7, v80
	v_lshl_add_u64 v[80:81], s[30:31], 0, v[180:181]
	v_add_co_u32_e32 v80, vcc, 0x40000, v80
	global_load_dwordx4 v[168:171], v82, s[10:11]
	global_load_dwordx4 v[172:175], v82, s[10:11] offset:128
	global_load_dwordx4 v[160:163], v180, s[30:31]
	v_addc_co_u32_e32 v81, vcc, 0, v81, vcc
	global_load_dwordx4 v[176:179], v83, s[16:17]
	global_load_dwordx4 v[164:167], v[80:81], off
	s_waitcnt lgkmcnt(0)
	s_barrier
	s_add_i32 s10, s40, 1
	s_cmp_gt_i32 s10, s38
	s_cbranch_scc1 .LBB0_979
	ds_read_b128 v[80:83], v207 offset:44032
	ds_read_b128 v[212:215], v207 offset:44064
	ds_read_b128 v[220:223], v207 offset:56832
	ds_read_b128 v[224:227], v207 offset:56864
	s_waitcnt lgkmcnt(3)
	v_mfma_f32_32x32x16_bf16 v[96:111], v[80:83], v[112:115], v[64:79]
	s_waitcnt lgkmcnt(1)
	v_mfma_f32_32x32x16_bf16 v[80:95], v[220:223], v[112:115], v[64:79]
	ds_read_b128 v[220:223], v207 offset:44096
	ds_read_b128 v[228:231], v207 offset:56896
	v_mfma_f32_32x32x16_bf16 v[96:111], v[212:215], v[116:119], v[96:111]
	s_waitcnt lgkmcnt(2)
	v_mfma_f32_32x32x16_bf16 v[80:95], v[224:227], v[116:119], v[80:95]
	ds_read_b128 v[212:215], v207 offset:44128
	ds_read_b128 v[224:227], v207 offset:56928
	s_waitcnt lgkmcnt(3)
	v_mfma_f32_32x32x16_bf16 v[96:111], v[220:223], v[120:123], v[96:111]
	s_waitcnt lgkmcnt(2)
	v_mfma_f32_32x32x16_bf16 v[80:95], v[228:231], v[120:123], v[80:95]
	ds_read_b128 v[220:223], v207 offset:44160
	ds_read_b128 v[228:231], v207 offset:56960
	s_waitcnt lgkmcnt(3)
	v_mfma_f32_32x32x16_bf16 v[96:111], v[212:215], v[124:127], v[96:111]
	s_waitcnt lgkmcnt(2)
	v_mfma_f32_32x32x16_bf16 v[80:95], v[224:227], v[124:127], v[80:95]
	ds_read_b128 v[212:215], v207 offset:44192
	ds_read_b128 v[224:227], v207 offset:56992
	s_waitcnt lgkmcnt(3)
	v_mfma_f32_32x32x16_bf16 v[96:111], v[220:223], v[128:131], v[96:111]
	s_waitcnt lgkmcnt(2)
	v_mfma_f32_32x32x16_bf16 v[80:95], v[228:231], v[128:131], v[80:95]
	ds_read_b128 v[220:223], v207 offset:44224
	ds_read_b128 v[228:231], v207 offset:57024
	s_waitcnt lgkmcnt(3)
	v_mfma_f32_32x32x16_bf16 v[96:111], v[212:215], v[132:135], v[96:111]
	s_waitcnt lgkmcnt(2)
	v_mfma_f32_32x32x16_bf16 v[80:95], v[224:227], v[132:135], v[80:95]
	ds_read_b128 v[212:215], v207 offset:44256
	ds_read_b128 v[224:227], v207 offset:57056
	s_waitcnt lgkmcnt(3)
	v_mfma_f32_32x32x16_bf16 v[96:111], v[220:223], v[136:139], v[96:111]
	s_waitcnt lgkmcnt(2)
	v_mfma_f32_32x32x16_bf16 v[80:95], v[228:231], v[136:139], v[80:95]
	ds_read_b128 v[220:223], v207 offset:44288
	ds_read_b128 v[228:231], v207 offset:57088
	s_waitcnt lgkmcnt(3)
	v_mfma_f32_32x32x16_bf16 v[96:111], v[212:215], v[140:143], v[96:111]
	s_waitcnt lgkmcnt(2)
	v_mfma_f32_32x32x16_bf16 v[80:95], v[224:227], v[140:143], v[80:95]
	ds_read_b128 v[212:215], v207 offset:44320
	ds_read_b128 v[224:227], v207 offset:57120
	s_waitcnt lgkmcnt(3)
	v_mfma_f32_32x32x16_bf16 v[96:111], v[220:223], v[144:147], v[96:111]
	s_waitcnt lgkmcnt(2)
	v_mfma_f32_32x32x16_bf16 v[80:95], v[228:231], v[144:147], v[80:95]
	ds_read_b128 v[220:223], v207 offset:44352
	ds_read_b128 v[228:231], v207 offset:57152
	s_waitcnt lgkmcnt(3)
	v_mfma_f32_32x32x16_bf16 v[96:111], v[212:215], v[148:151], v[96:111]
	s_waitcnt lgkmcnt(2)
	v_mfma_f32_32x32x16_bf16 v[80:95], v[224:227], v[148:151], v[80:95]
	ds_read_b128 v[212:215], v207 offset:44384
	ds_read_b128 v[224:227], v207 offset:57184
	s_waitcnt lgkmcnt(3)
	v_mfma_f32_32x32x16_bf16 v[96:111], v[220:223], v[152:155], v[96:111]
	s_waitcnt lgkmcnt(2)
	v_mfma_f32_32x32x16_bf16 v[80:95], v[228:231], v[152:155], v[80:95]
	s_waitcnt lgkmcnt(1)
	v_mfma_f32_32x32x16_bf16 v[96:111], v[212:215], v[156:159], v[96:111]
	s_waitcnt lgkmcnt(0)
	v_mfma_f32_32x32x16_bf16 v[80:95], v[224:227], v[156:159], v[80:95]
	s_add_i32 s10, s40, 64
	s_cmp_le_i32 s10, s1
	s_nop 15
	s_nop 7
	s_cbranch_scc1 .LBB0_976
	v_add_u32_e32 v180, s40, v199
	v_add_u32_e32 v203, 33, v180
	v_add_u32_e32 v202, 1, v180
	v_cmp_le_i32_e32 vcc, v203, v198
	s_nop 4
	v_cndmask_b32_e32 v80, v204, v80, vcc
	v_cmp_lt_i32_e32 vcc, v202, v198
	s_nop 1
	v_cndmask_b32_e32 v97, v204, v97, vcc
	v_cmp_le_i32_e32 vcc, v202, v198
	v_add_u32_e32 v202, 34, v180
	s_nop 0
	v_cndmask_b32_e32 v96, v204, v96, vcc
	v_cmp_le_i32_e32 vcc, v202, v198
	v_add_u32_e32 v202, 3, v180
	s_nop 0
	v_cndmask_b32_e32 v81, v204, v81, vcc
	v_cmp_le_i32_e32 vcc, v202, v198
	v_add_u32_e32 v202, 35, v180
	s_nop 0
	v_cndmask_b32_e32 v98, v204, v98, vcc
	v_cmp_le_i32_e32 vcc, v202, v198
	v_add_u32_e32 v202, 4, v180
	s_nop 0
	v_cndmask_b32_e32 v82, v204, v82, vcc
	v_cmp_le_i32_e32 vcc, v202, v198
	v_add_u32_e32 v202, 36, v180
	s_nop 0
	v_cndmask_b32_e32 v99, v204, v99, vcc
	v_cmp_le_i32_e32 vcc, v202, v198
	v_add_u32_e32 v202, 9, v180
	s_nop 0
	v_cndmask_b32_e32 v83, v204, v83, vcc
	v_cmp_le_i32_e32 vcc, v202, v198
	v_add_u32_e32 v202, 41, v180
	s_nop 0
	v_cndmask_b32_e32 v100, v204, v100, vcc
	v_cmp_le_i32_e32 vcc, v202, v198
	v_add_u32_e32 v202, 10, v180
	s_nop 0
	v_cndmask_b32_e32 v84, v204, v84, vcc
	v_cmp_le_i32_e32 vcc, v202, v198
	v_add_u32_e32 v202, 42, v180
	s_nop 0
	v_cndmask_b32_e32 v101, v204, v101, vcc
	v_cmp_le_i32_e32 vcc, v202, v198
	v_add_u32_e32 v202, 11, v180
	s_nop 0
	v_cndmask_b32_e32 v85, v204, v85, vcc
	v_cmp_le_i32_e32 vcc, v202, v198
	v_add_u32_e32 v202, 43, v180
	s_nop 0
	v_cndmask_b32_e32 v102, v204, v102, vcc
	v_cmp_le_i32_e32 vcc, v202, v198
	v_add_u32_e32 v202, 12, v180
	s_nop 0
	v_cndmask_b32_e32 v86, v204, v86, vcc
	v_cmp_le_i32_e32 vcc, v202, v198
	v_add_u32_e32 v202, 44, v180
	s_nop 0
	v_cndmask_b32_e32 v103, v204, v103, vcc
	v_cmp_le_i32_e32 vcc, v202, v198
	v_add_u32_e32 v202, 17, v180
	s_nop 0
	v_cndmask_b32_e32 v87, v204, v87, vcc
	v_cmp_le_i32_e32 vcc, v202, v198
	v_add_u32_e32 v202, 49, v180
	s_nop 0
	v_cndmask_b32_e32 v104, v204, v104, vcc
	v_cmp_le_i32_e32 vcc, v202, v198
	v_add_u32_e32 v202, 18, v180
	s_nop 0
	v_cndmask_b32_e32 v88, v204, v88, vcc
	v_cmp_le_i32_e32 vcc, v202, v198
	v_add_u32_e32 v202, 50, v180
	s_nop 0
	v_cndmask_b32_e32 v105, v204, v105, vcc
	v_cmp_le_i32_e32 vcc, v202, v198
	v_add_u32_e32 v202, 19, v180
	s_nop 0
	v_cndmask_b32_e32 v89, v204, v89, vcc
	v_cmp_le_i32_e32 vcc, v202, v198
	v_add_u32_e32 v202, 51, v180
	s_nop 0
	v_cndmask_b32_e32 v106, v204, v106, vcc
	v_cmp_le_i32_e32 vcc, v202, v198
	v_add_u32_e32 v202, 20, v180
	s_nop 0
	v_cndmask_b32_e32 v90, v204, v90, vcc
	v_cmp_le_i32_e32 vcc, v202, v198
	v_add_u32_e32 v202, 52, v180
	s_nop 0
	v_cndmask_b32_e32 v107, v204, v107, vcc
	v_cmp_le_i32_e32 vcc, v202, v198
	v_add_u32_e32 v202, 25, v180
	s_nop 0
	v_cndmask_b32_e32 v91, v204, v91, vcc
	v_cmp_le_i32_e32 vcc, v202, v198
	v_add_u32_e32 v202, 57, v180
	s_nop 0
	v_cndmask_b32_e32 v108, v204, v108, vcc
	v_cmp_le_i32_e32 vcc, v202, v198
	v_add_u32_e32 v202, 26, v180
	s_nop 0
	v_cndmask_b32_e32 v92, v204, v92, vcc
	v_cmp_le_i32_e32 vcc, v202, v198
	v_add_u32_e32 v202, 58, v180
	s_nop 0
	v_cndmask_b32_e32 v109, v204, v109, vcc
	v_cmp_le_i32_e32 vcc, v202, v198
	v_add_u32_e32 v202, 27, v180
	s_nop 0
	v_cndmask_b32_e32 v93, v204, v93, vcc
	v_cmp_le_i32_e32 vcc, v202, v198
	v_add_u32_e32 v202, 59, v180
	s_nop 0
	v_cndmask_b32_e32 v110, v204, v110, vcc
	v_cmp_le_i32_e32 vcc, v202, v198
	v_add_u32_e32 v202, 28, v180
	v_add_u32_e32 v180, 60, v180
	v_cndmask_b32_e32 v94, v204, v94, vcc
	v_cmp_le_i32_e32 vcc, v202, v198
	s_nop 1
	v_cndmask_b32_e32 v111, v204, v111, vcc
	v_cmp_le_i32_e32 vcc, v180, v198
	s_nop 1
	v_cndmask_b32_e32 v95, v204, v95, vcc

.LBB0_979:
	s_cmp_ge_u32 s36, s37
	s_cselect_b64 s[10:11], -1, 0
	s_and_b64 vcc, exec, s[10:11]
	s_cbranch_vccnz .LBB0_961
	v_mov_b32_e32 v80, v195
	s_nop 0
	v_lshrrev_b32_e32 v81, 3, v80
	v_mul_u32_u24_e32 v82, s51, v81
	v_lshlrev_b32_e32 v83, 4, v80
	v_mul_u32_u24_e32 v81, s5, v81
	v_lshlrev_b32_e32 v80, 3, v80
	v_and_b32_e32 v84, 0x70, v83
	v_and_b32_e32 v83, 0x60, v83
	v_and_b32_e32 v80, 8, v80
	v_add_u32_e32 v81, 0, v81
	v_add3_u32 v80, v81, v83, v80
	v_add3_u32 v82, 0, v82, v84
	v_add_u32_e32 v81, 0x6000, v80
	v_add_u32_e32 v80, 0x8800, v80
	s_waitcnt vmcnt(4)
	ds_write_b128 v82, v[168:171]
	s_waitcnt vmcnt(3)
	ds_write_b128 v82, v[172:175] offset:128
	s_waitcnt vmcnt(1)
	ds_write_b128 v82, v[176:179] offset:256
	ds_write2_b64 v81, v[160:161], v[162:163] offset0:128 offset1:130
	s_waitcnt vmcnt(0)
	ds_write2_b64 v80, v[164:165], v[166:167] offset1:2
	s_branch .LBB0_961
